# FOXIN epilogue: 8 ssq row loads issued together instead of serialized
# speedup vs baseline: 1.0047x; 1.0047x over previous
.LBB0_153:
	v_and_b32_e32 v49, 64, v217
	v_xor_b32_e32 v48, 16, v217
	v_add_u32_e32 v49, 64, v49
	v_cmp_lt_i32_e32 vcc, v48, v49
	s_lshl_b32 s81, s86, 8
	s_add_i32 s81, s81, s95
	v_cndmask_b32_e32 v48, v217, v48, vcc
	v_lshlrev_b32_e32 v220, 2, v48
	v_xor_b32_e32 v48, 32, v217
	v_or_b32_e32 v194, s81, v153
	v_cmp_lt_i32_e32 vcc, v48, v49
	v_ashrrev_i32_e32 v195, 31, v194
	v_or_b32_e32 v188, 16, v194
	v_cndmask_b32_e32 v48, v217, v48, vcc
	v_lshlrev_b32_e32 v221, 2, v48
	v_ashrrev_i32_e32 v189, 31, v188
	v_or_b32_e32 v186, 32, v194
	v_ashrrev_i32_e32 v187, 31, v186
	v_or_b32_e32 v180, 48, v194
	v_ashrrev_i32_e32 v181, 31, v180
	v_add_u32_e32 v178, 0x80, v194
	v_ashrrev_i32_e32 v179, 31, v178
	v_add_u32_e32 v172, 0x90, v194
	v_ashrrev_i32_e32 v173, 31, v172
	v_add_u32_e32 v170, 0xa0, v194
	v_ashrrev_i32_e32 v171, 31, v170
	v_add_u32_e32 v168, 0xb0, v194
	v_ashrrev_i32_e32 v169, 31, v168
	v_lshlrev_b64 v[48:49], 6, v[194:195]
	v_lshl_add_u64 v[48:49], v[156:157], 0, v[48:49]
	global_load_dwordx4 v[48:51], v[48:49], off
	v_lshlrev_b64 v[52:53], 6, v[188:189]
	v_lshl_add_u64 v[52:53], v[156:157], 0, v[52:53]
	global_load_dwordx4 v[52:55], v[52:53], off
	v_lshlrev_b64 v[56:57], 6, v[186:187]
	v_lshl_add_u64 v[56:57], v[156:157], 0, v[56:57]
	global_load_dwordx4 v[56:59], v[56:57], off
	v_lshlrev_b64 v[60:61], 6, v[180:181]
	v_lshl_add_u64 v[60:61], v[156:157], 0, v[60:61]
	global_load_dwordx4 v[60:63], v[60:61], off
	v_lshlrev_b64 v[232:233], 6, v[178:179]
	v_lshl_add_u64 v[232:233], v[156:157], 0, v[232:233]
	global_load_dwordx4 v[232:235], v[232:233], off
	v_lshlrev_b64 v[236:237], 6, v[172:173]
	v_lshl_add_u64 v[236:237], v[156:157], 0, v[236:237]
	global_load_dwordx4 v[236:239], v[236:237], off
	v_lshlrev_b64 v[240:241], 6, v[170:171]
	v_lshl_add_u64 v[240:241], v[156:157], 0, v[240:241]
	global_load_dwordx4 v[240:243], v[240:241], off
	v_lshlrev_b64 v[244:245], 6, v[168:169]
	v_lshl_add_u64 v[244:245], v[156:157], 0, v[244:245]
	global_load_dwordx4 v[244:247], v[244:245], off
	s_ashr_i32 s79, s92, 2
	s_cmp_gt_i32 s79, 1
	s_cselect_b64 s[8:9], -1, 0
	s_and_b64 vcc, exec, s[8:9]
	s_waitcnt vmcnt(0)
	v_add_f32_e32 v48, v49, v48
	v_add_f32_e32 v49, v50, v51
	v_add_f32_e32 v52, v53, v52
	v_add_f32_e32 v53, v54, v55
	v_add_f32_e32 v50, v52, v53
	v_add_f32_e32 v51, v48, v49
	ds_bpermute_b32 v55, v220, v51
	ds_bpermute_b32 v54, v220, v50
	v_add_f32_e32 v56, v57, v56
	v_add_f32_e32 v57, v58, v59
	v_add_f32_e32 v60, v61, v60
	v_add_f32_e32 v61, v62, v63
	v_add_f32_e32 v58, v60, v61
	v_add_f32_e32 v59, v56, v57
	ds_bpermute_b32 v63, v220, v59
	ds_bpermute_b32 v62, v220, v58
	v_add_f32_e32 v232, v233, v232
	v_add_f32_e32 v233, v234, v235
	v_add_f32_e32 v236, v237, v236
	v_add_f32_e32 v237, v238, v239
	v_add_f32_e32 v234, v236, v237
	v_add_f32_e32 v235, v232, v233
	ds_bpermute_b32 v239, v220, v235
	ds_bpermute_b32 v238, v220, v234
	v_add_f32_e32 v240, v241, v240
	v_add_f32_e32 v241, v242, v243
	v_add_f32_e32 v244, v245, v244
	v_add_f32_e32 v245, v246, v247
	v_add_f32_e32 v242, v244, v245
	v_add_f32_e32 v243, v240, v241
	ds_bpermute_b32 v247, v220, v243
	ds_bpermute_b32 v246, v220, v242
	s_waitcnt lgkmcnt(6)
	v_pk_add_f32 v[196:197], v[50:51], v[54:55]
	ds_bpermute_b32 v199, v221, v197
	ds_bpermute_b32 v198, v221, v196
	s_waitcnt lgkmcnt(6)
	v_pk_add_f32 v[190:191], v[58:59], v[62:63]
	ds_bpermute_b32 v193, v221, v191
	ds_bpermute_b32 v192, v221, v190
	s_waitcnt lgkmcnt(6)
	v_pk_add_f32 v[182:183], v[234:235], v[238:239]
	ds_bpermute_b32 v185, v221, v183
	ds_bpermute_b32 v184, v221, v182
	s_waitcnt lgkmcnt(6)
	v_pk_add_f32 v[174:175], v[242:243], v[246:247]
	ds_bpermute_b32 v177, v221, v175
	ds_bpermute_b32 v176, v221, v174
	s_waitcnt lgkmcnt(2)
	s_cbranch_vccnz .LBB0_155
	s_cmp_lt_u32 s92, 4
	s_cselect_b32 s3, s63, s65
	s_cselect_b32 s2, s62, s64
	global_load_dwordx4 v[48:51], v218, s[2:3] offset:16
	global_load_dwordx4 v[56:59], v218, s[2:3]
	global_load_dwordx4 v[52:55], v218, s[2:3] offset:144
	global_load_dwordx4 v[60:63], v218, s[2:3] offset:128
